# v28: v26 + M1 item->unit mapping: fourth-round items run the cheap 16-token first-chunk units
# speedup vs baseline: 1.0053x; 1.0053x over previous
; DI UnitInfo decode_unit(int unit) {
;     UnitInfo u;
;     if (unit < NUNIT_P) { u.prompt = 1; u.b = unit / NCH; u.c = unit - u.b * NCH; u.s = 0; const int tau0 = u.c == 0 ? 0 : NMETA + 64 * (u.c - 1); u.nvalid = u.c == 0 ? NMETA : 64; u.row0 = u.b * LP + tau0; }
;     else { u.prompt = 0; u.s = unit - NUNIT_P; u.b = 0; u.c = 0; u.row0 = MP + LS * u.s; u.nvalid = LS; }
;     return u;
; template <bool FINAL>
; DI void gla_unit(KA a, int l, int item, LAS unsigned char* lds) {
;     const int unit = item >> 1, hp = item & 1;
;     const UnitInfo u = decode_unit(unit);
.LBB0_603:
	s_ashr_i32 s50, s33, 1
	s_cmpk_lt_i32 s50, 0x180
	s_cbranch_scc1 .Lm1_map_lo
	s_sub_i32 s50, s50, 0x180
	s_mul_i32 s50, s50, 33
	s_branch .Lm1_map_done
.Lm1_map_lo:
	s_cmpk_lt_i32 s50, 0x108
	s_cbranch_scc0 .Lm1_map_done
	s_mul_hi_i32 s4, s50, 0x3e0f83e1
	s_lshr_b32 s5, s4, 31
	s_ashr_i32 s4, s4, 3
	s_add_i32 s4, s4, s5
	s_mul_i32 s5, s4, 33
	s_cmp_eq_u32 s5, s50
	s_cbranch_scc0 .Lm1_map_done
	s_add_i32 s50, s4, 0x180
.Lm1_map_done:
	s_cmpk_gt_i32 s50, 0x107
	v_readlane_b32 s2, v254, 4
	s_cselect_b64 s[4:5], -1, 0
	s_cmpk_lt_i32 s50, 0x108
	v_readlane_b32 s3, v254, 5
	s_cselect_b64 s[30:31], -1, 0
	s_mov_b64 s[6:7], -1
	s_and_b64 vcc, exec, s[4:5]
	s_cbranch_vccnz .LBB0_605
	s_mul_hi_i32 s0, s50, 0x3e0f83e1
	s_lshr_b32 s6, s0, 31
	s_ashr_i32 s0, s0, 3
	s_add_i32 s6, s0, s6
	s_mul_i32 s0, s6, 0xffffffdf
	s_add_i32 s0, s0, s50
	s_lshl_b32 s7, s0, 6
	s_sub_i32 s7, s7, 48
	s_cmp_eq_u32 s0, 0
	s_cselect_b32 s7, 0, s7
	s_mulk_i32 s6, 0x810
	s_cselect_b32 s0, 16, 64
	s_add_i32 s51, s7, s6
	s_mov_b64 s[6:7], 0
